# follower L1 invalidate also skipped after the S5 phases (z lines are written by a single workgroup)
# speedup vs baseline: 1.0259x; 1.0259x over previous
.Lxbar_follow:
	s_movk_i32 s99, 0x556
	s_bitcmp1_b32 s99, s98
	s_cbranch_scc1 .Lxbar_noinv
	buffer_inv sc1
